# attention per-query softmax denominator reduced with permlane16/32 swaps instead of two ds_bpermute round trips
# baseline (speedup 1.0000x reference)
.Latt_nonext:
	v_mov_b32_e32 v73, v72
	v_mov_b32_e32 v124, v123
	v_mov_b32_e32 v125, v122
	v_permlane16_swap_b32 v73, v72
	v_mov_b32_e32 v126, v121
	v_mov_b32_e32 v127, v120
	v_add_f32_e32 v72, v72, v73
	s_mov_b32 s2, s25
	v_mov_b32_e32 v73, v72
	s_nop 1
	v_permlane32_swap_b32 v73, v72
	v_add_f32_e32 v72, v72, v73
	v_div_scale_f32 v73, s[0:1], v72, v72, 1.0
	v_rcp_f32_e32 v74, v73
	s_lshl_b64 s[0:1], s[76:77], 13
	s_mov_b32 s76, s38
	v_fma_f32 v75, -v73, v74, 1.0
	v_fmac_f32_e32 v74, v75, v74
	v_div_scale_f32 v75, vcc, 1.0, v72, 1.0
	v_mul_f32_e32 v76, v75, v74
	v_fma_f32 v77, -v73, v76, v75
	v_fmac_f32_e32 v76, v77, v74
	v_fma_f32 v73, -v73, v76, v75
	v_div_fmas_f32 v73, v73, v74, v76
	v_div_fixup_f32 v72, v73, v72, 1.0
	v_pk_mul_f32 v[24:25], v[24:25], v[72:73] op_sel_hi:[1,0]
	v_pk_mul_f32 v[26:27], v[26:27], v[72:73] op_sel_hi:[1,0]
	v_lshl_add_u64 v[74:75], v[104:105], 0, s[0:1]
	v_cvt_pk_bf16_f32 v24, v24, v25
	v_cvt_pk_bf16_f32 v25, v26, v27
	global_store_dwordx2 v[74:75], v[24:25], off offset:32
	v_pk_mul_f32 v[24:25], v[64:65], v[72:73] op_sel_hi:[1,0]
	v_pk_mul_f32 v[26:27], v[66:67], v[72:73] op_sel_hi:[1,0]
	v_cvt_pk_bf16_f32 v24, v24, v25
	v_cvt_pk_bf16_f32 v25, v26, v27
	global_store_dwordx2 v[74:75], v[24:25], off offset:64
	v_pk_mul_f32 v[24:25], v[60:61], v[72:73] op_sel_hi:[1,0]
	v_pk_mul_f32 v[26:27], v[62:63], v[72:73] op_sel_hi:[1,0]
	v_cvt_pk_bf16_f32 v24, v24, v25
	v_cvt_pk_bf16_f32 v25, v26, v27
	global_store_dwordx2 v[74:75], v[24:25], off offset:96
	v_pk_mul_f32 v[24:25], v[56:57], v[72:73] op_sel_hi:[1,0]
	v_pk_mul_f32 v[26:27], v[58:59], v[72:73] op_sel_hi:[1,0]
	v_cvt_pk_bf16_f32 v24, v24, v25
	v_cvt_pk_bf16_f32 v25, v26, v27
	global_store_dwordx2 v[74:75], v[24:25], off offset:128
	v_pk_mul_f32 v[24:25], v[52:53], v[72:73] op_sel_hi:[1,0]
	v_pk_mul_f32 v[26:27], v[54:55], v[72:73] op_sel_hi:[1,0]
	v_cvt_pk_bf16_f32 v24, v24, v25
	v_cvt_pk_bf16_f32 v25, v26, v27
	global_store_dwordx2 v[74:75], v[24:25], off offset:160
	v_pk_mul_f32 v[24:25], v[48:49], v[72:73] op_sel_hi:[1,0]
	v_pk_mul_f32 v[26:27], v[50:51], v[72:73] op_sel_hi:[1,0]
	v_cvt_pk_bf16_f32 v24, v24, v25
	v_cvt_pk_bf16_f32 v25, v26, v27
	global_store_dwordx2 v[74:75], v[24:25], off offset:192
	v_pk_mul_f32 v[24:25], v[44:45], v[72:73] op_sel_hi:[1,0]
	v_pk_mul_f32 v[26:27], v[46:47], v[72:73] op_sel_hi:[1,0]
	v_cvt_pk_bf16_f32 v24, v24, v25
	v_cvt_pk_bf16_f32 v25, v26, v27
	global_store_dwordx2 v[74:75], v[24:25], off offset:224
	v_pk_mul_f32 v[24:25], v[40:41], v[72:73] op_sel_hi:[1,0]
	v_pk_mul_f32 v[26:27], v[42:43], v[72:73] op_sel_hi:[1,0]
	v_cvt_pk_bf16_f32 v24, v24, v25
	v_cvt_pk_bf16_f32 v25, v26, v27
	v_pk_mul_f32 v[68:69], v[68:69], v[72:73] op_sel_hi:[1,0]
	v_pk_mul_f32 v[70:71], v[70:71], v[72:73] op_sel_hi:[1,0]
	global_store_dwordx2 v[74:75], v[24:25], off offset:256
	v_pk_mul_f32 v[24:25], v[28:29], v[72:73] op_sel_hi:[1,0]
	v_pk_mul_f32 v[26:27], v[30:31], v[72:73] op_sel_hi:[1,0]
	v_pk_mul_f32 v[20:21], v[20:21], v[72:73] op_sel_hi:[1,0]
	v_pk_mul_f32 v[22:23], v[22:23], v[72:73] op_sel_hi:[1,0]
	v_pk_mul_f32 v[16:17], v[16:17], v[72:73] op_sel_hi:[1,0]
	v_pk_mul_f32 v[18:19], v[18:19], v[72:73] op_sel_hi:[1,0]
	v_pk_mul_f32 v[12:13], v[12:13], v[72:73] op_sel_hi:[1,0]
	v_pk_mul_f32 v[14:15], v[14:15], v[72:73] op_sel_hi:[1,0]
	v_pk_mul_f32 v[8:9], v[8:9], v[72:73] op_sel_hi:[1,0]
	v_pk_mul_f32 v[10:11], v[10:11], v[72:73] op_sel_hi:[1,0]
	v_pk_mul_f32 v[4:5], v[4:5], v[72:73] op_sel_hi:[1,0]
	v_pk_mul_f32 v[6:7], v[6:7], v[72:73] op_sel_hi:[1,0]
	v_pk_mul_f32 v[0:1], v[0:1], v[72:73] op_sel_hi:[1,0]
	v_pk_mul_f32 v[2:3], v[2:3], v[72:73] op_sel_hi:[1,0]
	v_cvt_pk_bf16_f32 v68, v68, v69
	v_cvt_pk_bf16_f32 v69, v70, v71
	v_cvt_pk_bf16_f32 v24, v24, v25
	v_cvt_pk_bf16_f32 v25, v26, v27
	v_cvt_pk_bf16_f32 v20, v20, v21
	v_cvt_pk_bf16_f32 v21, v22, v23
	v_cvt_pk_bf16_f32 v16, v16, v17
	v_cvt_pk_bf16_f32 v17, v18, v19
	v_cvt_pk_bf16_f32 v12, v12, v13
	v_cvt_pk_bf16_f32 v13, v14, v15
	v_cvt_pk_bf16_f32 v8, v8, v9
	v_cvt_pk_bf16_f32 v9, v10, v11
	v_cvt_pk_bf16_f32 v4, v4, v5
	v_cvt_pk_bf16_f32 v5, v6, v7
	v_cvt_pk_bf16_f32 v0, v0, v1
	v_cvt_pk_bf16_f32 v1, v2, v3
	s_and_b64 vcc, exec, s[40:41]
	global_store_dwordx2 v[74:75], v[68:69], off
	global_store_dwordx2 v[74:75], v[24:25], off offset:288
	global_store_dwordx2 v[74:75], v[20:21], off offset:320
	global_store_dwordx2 v[74:75], v[16:17], off offset:352
	global_store_dwordx2 v[74:75], v[12:13], off offset:384
	global_store_dwordx2 v[74:75], v[8:9], off offset:416
	global_store_dwordx2 v[74:75], v[4:5], off offset:448
	global_store_dwordx2 v[74:75], v[0:1], off offset:480
	s_cbranch_vccz .LBB0_128
